# rmsnorm(mem_prompt) rows moved from P0 to the side CUs (hand-written wave-per-row routine, published with the w_mem_k/v copies)
# speedup vs baseline: 1.0034x; 1.0034x over previous
; #define GAS __attribute__((address_space(1)))
; __device__ __forceinline__ unsigned cvt_pk_bf16(float lo, float hi) { unsigned r; asm volatile("v_cvt_pk_bf16_f32 %0, %1, %2" : "=v"(r) : "v"(lo), "v"(hi)); return r; }
; __device__ __forceinline__ void rms_row_to_bf16(const float* xrow, const float* g, bf16_t* orow, int lane) {
;     const GAS f32x4* xr = (const GAS f32x4*)xrow + lane;
;     f32x4 v[16], gv[16]; float s = 0.f;
;     const GAS f32x4* gr = (const GAS f32x4*)g + lane;
; #pragma unroll
;     for (int j = 0; j < 16; ++j) v[j] = __builtin_nontemporal_load(xr + 64 * j);
; #pragma unroll
;     for (int j = 0; j < 16; ++j) gv[j] = gr[64 * j];
; #pragma unroll
;     for (int j = 0; j < 16; ++j) s += (v[j].x * v[j].x + v[j].y * v[j].y) + (v[j].z * v[j].z + v[j].w * v[j].w);
;     const float rstd = 1.0f / sqrtf(wave_sum(s) * (1.0f / DM) + EPS);
;     GAS u32x2* o8 = (GAS u32x2*)orow + lane;
; #pragma unroll
;     for (int j = 0; j < 16; ++j) { const f32x4 gg = gv[j]; u32x2 w; w.x = cvt_pk_bf16(v[j].x * rstd * gg.x, v[j].y * rstd * gg.y); w.y = cvt_pk_bf16(v[j].z * rstd * gg.z, v[j].w * rstd * gg.w); o8[64 * j] = w; }
; }
; __device__ __forceinline__ void p0_prologue(Frame& F, bool all_weights) {
;     ...
;     for (int m = gw; m < MT + MM; m += NGW) {
;         if (m < MP) rms_row_to_bf16(F.in[0] + (size_t)m * DM, F.in[7], H + (size_t)m * DM, F.lane);
;         else if (m < MT) rms_row_to_bf16(F.in[2] + (size_t)(m - MP) * DM, F.in[7], H + (size_t)m * DM, F.lane);
;         else rms_row_to_bf16(F.in[1] + (size_t)(m - MT) * DM, F.in[8], HM + (size_t)(m - MT) * DM, F.lane);
;     }
.LBB0_43:
	s_cmpk_gt_i32 s40, 0x21ff
	s_cbranch_scc1 .LBB0_54
	v_lshlrev_b32_e32 v2, 4, v1
	v_mov_b32_e32 v3, 0
	s_waitcnt lgkmcnt(0)
	v_lshl_add_u64 v[94:95], s[6:7], 0, v[2:3]
	s_mov_b64 s[6:7], 0x1000
	v_lshl_add_u64 v[120:121], s[4:5], 0, v[2:3]
	v_lshl_add_u64 v[96:97], v[94:95], 0, s[6:7]
	s_mov_b64 s[8:9], 0x1400
	v_lshl_add_u64 v[122:123], v[120:121], 0, s[6:7]
	s_lshl_b32 s6, s12, 16
	s_lshl_b32 s7, s13, 13
	s_ashr_i32 s41, s40, 31
	v_lshl_add_u64 v[98:99], v[94:95], 0, s[8:9]
	v_lshl_add_u64 v[124:125], v[120:121], 0, s[8:9]
	v_mov_b32_e32 v7, v3
	s_add_i32 s6, s6, s7
	s_lshl_b32 s12, s3, 16
	s_lshl_b64 s[8:9], s[40:41], 13
	v_lshl_add_u64 v[4:5], s[42:43], 0, v[6:7]
	s_mov_b64 s[4:5], 0x1b200000
	s_add_u32 s8, s42, s8
	v_lshl_add_u64 v[148:149], v[4:5], 0, s[4:5]
	s_mov_b64 s[4:5], 0x1ba00000
	s_addc_u32 s9, s43, s9
	v_lshl_add_u64 v[152:153], v[4:5], 0, s[4:5]
	v_lshl_add_u64 v[4:5], s[8:9], 0, v[6:7]
	s_ashr_i32 s29, s28, 31
	v_lshl_add_u64 v[154:155], v[4:5], 0, s[4:5]
	s_lshl_b64 s[8:9], s[28:29], 13
	s_lshl_b64 s[4:5], s[40:41], 14
	s_add_u32 s4, s16, s4
	s_mov_b64 s[10:11], 0x1800
	s_mov_b64 s[20:21], 0x1c00
	s_mov_b64 s[22:23], 0x2000
	s_mov_b64 s[24:25], 0x2400
	s_mov_b64 s[26:27], 0x2800
	s_mov_b64 s[34:35], 0x2c00
	s_mov_b64 s[36:37], 0x3000
	s_mov_b64 s[46:47], 0x3400
	s_mov_b64 s[48:49], 0x3800
	s_mov_b64 s[50:51], 0x3c00
	s_addc_u32 s5, s17, s5
	v_lshl_add_u64 v[100:101], v[94:95], 0, s[10:11]
	v_lshl_add_u64 v[102:103], v[94:95], 0, s[20:21]
	v_lshl_add_u64 v[104:105], v[94:95], 0, s[22:23]
	v_lshl_add_u64 v[106:107], v[94:95], 0, s[24:25]
	v_lshl_add_u64 v[108:109], v[94:95], 0, s[26:27]
	v_lshl_add_u64 v[110:111], v[94:95], 0, s[34:35]
	v_lshl_add_u64 v[112:113], v[94:95], 0, s[36:37]
	v_lshl_add_u64 v[114:115], v[94:95], 0, s[46:47]
	v_lshl_add_u64 v[116:117], v[94:95], 0, s[48:49]
	v_lshl_add_u64 v[118:119], v[94:95], 0, s[50:51]
	v_lshl_add_u64 v[126:127], v[120:121], 0, s[10:11]
	v_lshl_add_u64 v[128:129], v[120:121], 0, s[20:21]
	v_lshl_add_u64 v[130:131], v[120:121], 0, s[22:23]
	v_lshl_add_u64 v[132:133], v[120:121], 0, s[24:25]
	v_lshl_add_u64 v[134:135], v[120:121], 0, s[26:27]
	v_lshl_add_u64 v[136:137], v[120:121], 0, s[34:35]
	v_lshl_add_u64 v[138:139], v[120:121], 0, s[36:37]
	v_lshl_add_u64 v[140:141], v[120:121], 0, s[46:47]
	v_lshl_add_u64 v[142:143], v[120:121], 0, s[48:49]
	v_lshl_add_u64 v[144:145], v[120:121], 0, s[50:51]
	v_lshl_add_u64 v[146:147], s[18:19], 0, v[2:3]
	v_lshl_add_u64 v[150:151], s[44:45], 0, v[2:3]
	v_lshl_add_u64 v[156:157], s[4:5], 0, v[2:3]
	s_lshl_b64 s[10:11], s[28:29], 14
	s_mov_b32 s17, 0
	s_movk_i32 s13, 0x1000
	v_mov_b32_e32 v1, 0x358637bd
	s_mov_b32 s18, 0xf800000
	v_mov_b32_e32 v160, 0x260
	v_mov_b32_e32 v161, 0x39800000
	s_branch .LBB0_46
.LBB0_45:
	v_add_co_u32_e32 v4, vcc, 0x1000, v158
	s_add_i32 s40, s40, s28
	s_add_i32 s6, s6, s12
	v_addc_co_u32_e32 v5, vcc, 0, v159, vcc
	v_lshl_add_u64 v[154:155], v[154:155], 0, s[8:9]
	s_cmpk_lt_i32 s40, 0x2200
	v_lshl_add_u64 v[156:157], v[156:157], 0, s[10:11]
	global_store_dwordx2 v[4:5], v[2:3], off offset:3584
	s_cbranch_scc0 .LBB0_54

; #define GAS __attribute__((address_space(1)))
; __device__ __forceinline__ void rms_row_to_bf16(const float* xrow, const float* g, bf16_t* orow, int lane) {
;     const GAS f32x4* xr = (const GAS f32x4*)xrow + lane;
;     f32x4 v[16], gv[16]; float s = 0.f;
;     const GAS f32x4* gr = (const GAS f32x4*)g + lane;
; #pragma unroll
;     for (int j = 0; j < 16; ++j) v[j] = __builtin_nontemporal_load(xr + 64 * j);
; #pragma unroll
;     for (int j = 0; j < 16; ++j) gv[j] = gr[64 * j];
; #pragma unroll
;     for (int j = 0; j < 16; ++j) s += (v[j].x * v[j].x + v[j].y * v[j].y) + (v[j].z * v[j].z + v[j].w * v[j].w);
;     const float rstd = 1.0f / sqrtf(wave_sum(s) * (1.0f / DM) + EPS);
.LBB0_316:
	s_cmpk_lt_u32 s54, 0x2e00
	s_cbranch_scc1 .Lkv_nopub
	s_bitcmp1_b32 s98, 4
	s_cbranch_scc1 .Lkv_nopub
	s_bitset1_b32 s98, 4
	s_sub_u32 s99, s54, 0x2e00
	s_load_dwordx2 s[100:101], s[0:1], 0x40
	v_and_b32_e32 v192, 63, v0
	v_lshlrev_b32_e32 v194, 4, v192
	v_mov_b32_e32 v195, 0
	v_lshlrev_b32_e32 v202, 3, v192
	v_mov_b32_e32 v203, 0
	v_mov_b32_e32 v207, 0
	v_mov_b32_e32 v216, 0x358637bd
	v_mov_b32_e32 v217, 0x39800000
	v_mov_b32_e32 v218, 0x260
	v_mov_b32_e32 v219, 0xf800000
	s_waitcnt lgkmcnt(0)
	v_lshl_add_u64 v[196:197], s[100:101], 0, v[194:195]
	s_load_dwordx2 s[100:101], s[0:1], 0x8
	global_load_dwordx4 v[128:131], v[196:197], off offset:0
	global_load_dwordx4 v[132:135], v[196:197], off offset:1024
	global_load_dwordx4 v[136:139], v[196:197], off offset:2048
	global_load_dwordx4 v[140:143], v[196:197], off offset:3072
	v_add_co_u32_e32 v196, vcc, 0x1000, v196
	s_nop 1
	v_addc_co_u32_e32 v197, vcc, 0, v197, vcc
	global_load_dwordx4 v[144:147], v[196:197], off offset:0
	global_load_dwordx4 v[148:151], v[196:197], off offset:1024
	global_load_dwordx4 v[152:155], v[196:197], off offset:2048
	global_load_dwordx4 v[156:159], v[196:197], off offset:3072
	v_add_co_u32_e32 v196, vcc, 0x1000, v196
	s_nop 1
	v_addc_co_u32_e32 v197, vcc, 0, v197, vcc
	global_load_dwordx4 v[160:163], v[196:197], off offset:0
	global_load_dwordx4 v[164:167], v[196:197], off offset:1024
	global_load_dwordx4 v[168:171], v[196:197], off offset:2048
	global_load_dwordx4 v[172:175], v[196:197], off offset:3072
	v_add_co_u32_e32 v196, vcc, 0x1000, v196
	s_nop 1
	v_addc_co_u32_e32 v197, vcc, 0, v197, vcc
	global_load_dwordx4 v[176:179], v[196:197], off offset:0
	global_load_dwordx4 v[180:183], v[196:197], off offset:1024
	global_load_dwordx4 v[184:187], v[196:197], off offset:2048
	global_load_dwordx4 v[188:191], v[196:197], off offset:3072
	s_waitcnt lgkmcnt(0)
	v_lshl_add_u64 v[208:209], s[100:101], 0, v[194:195]
	s_add_u32 s100, s6, 0x1b200000
	s_addc_u32 s101, s7, 0
	v_lshl_add_u64 v[210:211], s[100:101], 0, v[202:203]
.Lhm_row:
	v_mov_b32_e32 v206, s99
	v_lshlrev_b32_e32 v204, 13, v206
	v_mov_b32_e32 v205, 0
	v_lshlrev_b32_e32 v206, 14, v206
	v_lshl_add_u64 v[198:199], v[208:209], 0, v[206:207]
	v_lshl_add_u64 v[200:201], v[210:211], 0, v[204:205]
	global_load_dwordx4 v[62:65], v[198:199], off offset:0 nt
	global_load_dwordx4 v[66:69], v[198:199], off offset:1024 nt
	global_load_dwordx4 v[70:73], v[198:199], off offset:2048 nt
	global_load_dwordx4 v[74:77], v[198:199], off offset:3072 nt
	v_add_co_u32_e32 v198, vcc, 0x1000, v198
	s_nop 1
	v_addc_co_u32_e32 v199, vcc, 0, v199, vcc
	global_load_dwordx4 v[78:81], v[198:199], off offset:0 nt
	global_load_dwordx4 v[82:85], v[198:199], off offset:1024 nt
	global_load_dwordx4 v[86:89], v[198:199], off offset:2048 nt
	global_load_dwordx4 v[90:93], v[198:199], off offset:3072 nt
	v_add_co_u32_e32 v198, vcc, 0x1000, v198
	s_nop 1
	v_addc_co_u32_e32 v199, vcc, 0, v199, vcc
	global_load_dwordx4 v[94:97], v[198:199], off offset:0 nt
	global_load_dwordx4 v[98:101], v[198:199], off offset:1024 nt
	global_load_dwordx4 v[102:105], v[198:199], off offset:2048 nt
	global_load_dwordx4 v[106:109], v[198:199], off offset:3072 nt
	v_add_co_u32_e32 v198, vcc, 0x1000, v198
	s_nop 1
	v_addc_co_u32_e32 v199, vcc, 0, v199, vcc
	global_load_dwordx4 v[110:113], v[198:199], off offset:0 nt
	global_load_dwordx4 v[114:117], v[198:199], off offset:1024 nt
	global_load_dwordx4 v[118:121], v[198:199], off offset:2048 nt
	global_load_dwordx4 v[122:125], v[198:199], off offset:3072 nt
	v_mov_b32_e32 v212, 0
	s_waitcnt vmcnt(0)
	v_mul_f32_e32 v213, v63, v63
	v_fmac_f32_e32 v213, v62, v62
	v_mul_f32_e32 v214, v65, v65
	v_fmac_f32_e32 v214, v64, v64
	v_add_f32_e32 v213, v213, v214
	v_add_f32_e32 v212, v212, v213
	v_mul_f32_e32 v213, v67, v67
	v_fmac_f32_e32 v213, v66, v66
	v_mul_f32_e32 v214, v69, v69
	v_fmac_f32_e32 v214, v68, v68
	v_add_f32_e32 v213, v213, v214
	v_add_f32_e32 v212, v212, v213
	v_mul_f32_e32 v213, v71, v71
	v_fmac_f32_e32 v213, v70, v70
	v_mul_f32_e32 v214, v73, v73
	v_fmac_f32_e32 v214, v72, v72
	v_add_f32_e32 v213, v213, v214
	v_add_f32_e32 v212, v212, v213
	v_mul_f32_e32 v213, v75, v75
	v_fmac_f32_e32 v213, v74, v74
	v_mul_f32_e32 v214, v77, v77
	v_fmac_f32_e32 v214, v76, v76
	v_add_f32_e32 v213, v213, v214
	v_add_f32_e32 v212, v212, v213
	v_mul_f32_e32 v213, v79, v79
	v_fmac_f32_e32 v213, v78, v78
	v_mul_f32_e32 v214, v81, v81
	v_fmac_f32_e32 v214, v80, v80
	v_add_f32_e32 v213, v213, v214
	v_add_f32_e32 v212, v212, v213
	v_mul_f32_e32 v213, v83, v83
	v_fmac_f32_e32 v213, v82, v82
	v_mul_f32_e32 v214, v85, v85
	v_fmac_f32_e32 v214, v84, v84
	v_add_f32_e32 v213, v213, v214
	v_add_f32_e32 v212, v212, v213
	v_mul_f32_e32 v213, v87, v87
	v_fmac_f32_e32 v213, v86, v86
	v_mul_f32_e32 v214, v89, v89
	v_fmac_f32_e32 v214, v88, v88
	v_add_f32_e32 v213, v213, v214
	v_add_f32_e32 v212, v212, v213
	v_mul_f32_e32 v213, v91, v91
	v_fmac_f32_e32 v213, v90, v90
	v_mul_f32_e32 v214, v93, v93
	v_fmac_f32_e32 v214, v92, v92
	v_add_f32_e32 v213, v213, v214
	v_add_f32_e32 v212, v212, v213
	v_mul_f32_e32 v213, v95, v95
	v_fmac_f32_e32 v213, v94, v94
	v_mul_f32_e32 v214, v97, v97
	v_fmac_f32_e32 v214, v96, v96
	v_add_f32_e32 v213, v213, v214
	v_add_f32_e32 v212, v212, v213
	v_mul_f32_e32 v213, v99, v99
	v_fmac_f32_e32 v213, v98, v98
	v_mul_f32_e32 v214, v101, v101
	v_fmac_f32_e32 v214, v100, v100
	v_add_f32_e32 v213, v213, v214
	v_add_f32_e32 v212, v212, v213
	v_mul_f32_e32 v213, v103, v103
	v_fmac_f32_e32 v213, v102, v102
	v_mul_f32_e32 v214, v105, v105
	v_fmac_f32_e32 v214, v104, v104
	v_add_f32_e32 v213, v213, v214
	v_add_f32_e32 v212, v212, v213
; #define GAS __attribute__((address_space(1)))
; __device__ __forceinline__ unsigned cvt_pk_bf16(float lo, float hi) { unsigned r; asm volatile("v_cvt_pk_bf16_f32 %0, %1, %2" : "=v"(r) : "v"(lo), "v"(hi)); return r; }
; __device__ __forceinline__ void rms_row_to_bf16(const float* xrow, const float* g, bf16_t* orow, int lane) {
;     ...
;     for (int j = 0; j < 16; ++j) s += (v[j].x * v[j].x + v[j].y * v[j].y) + (v[j].z * v[j].z + v[j].w * v[j].w);
;     const float rstd = 1.0f / sqrtf(wave_sum(s) * (1.0f / DM) + EPS);
;     GAS u32x2* o8 = (GAS u32x2*)orow + lane;
; #pragma unroll
;     for (int j = 0; j < 16; ++j) { const f32x4 gg = gv[j]; u32x2 w; w.x = cvt_pk_bf16(v[j].x * rstd * gg.x, v[j].y * rstd * gg.y); w.y = cvt_pk_bf16(v[j].z * rstd * gg.z, v[j].w * rstd * gg.w); o8[64 * j] = w; }
	v_mul_f32_e32 v213, v107, v107
	v_fmac_f32_e32 v213, v106, v106
	v_mul_f32_e32 v214, v109, v109
	v_fmac_f32_e32 v214, v108, v108
	v_add_f32_e32 v213, v213, v214
	v_add_f32_e32 v212, v212, v213
	v_mul_f32_e32 v213, v111, v111
	v_fmac_f32_e32 v213, v110, v110
	v_mul_f32_e32 v214, v113, v113
	v_fmac_f32_e32 v214, v112, v112
	v_add_f32_e32 v213, v213, v214
	v_add_f32_e32 v212, v212, v213
	v_mul_f32_e32 v213, v115, v115
	v_fmac_f32_e32 v213, v114, v114
	v_mul_f32_e32 v214, v117, v117
	v_fmac_f32_e32 v214, v116, v116
	v_add_f32_e32 v213, v213, v214
	v_add_f32_e32 v212, v212, v213
	v_mul_f32_e32 v213, v119, v119
	v_fmac_f32_e32 v213, v118, v118
	v_mul_f32_e32 v214, v121, v121
	v_fmac_f32_e32 v214, v120, v120
	v_add_f32_e32 v213, v213, v214
	v_add_f32_e32 v212, v212, v213
	v_mul_f32_e32 v213, v123, v123
	v_fmac_f32_e32 v213, v122, v122
	v_mul_f32_e32 v214, v125, v125
	v_fmac_f32_e32 v214, v124, v124
	v_add_f32_e32 v213, v213, v214
	v_add_f32_e32 v212, v212, v213
	s_nop 1
	v_add_f32_dpp v212, v212, v212 quad_perm:[1,0,3,2] row_mask:0xf bank_mask:0xf bound_ctrl:1
	s_nop 1
	v_add_f32_dpp v212, v212, v212 quad_perm:[2,3,0,1] row_mask:0xf bank_mask:0xf bound_ctrl:1
	s_nop 1
	v_add_f32_dpp v212, v212, v212 row_half_mirror row_mask:0xf bank_mask:0xf bound_ctrl:1
	s_nop 1
	v_add_f32_dpp v212, v212, v212 row_mirror row_mask:0xf bank_mask:0xf bound_ctrl:1
	s_nop 1
	v_add_f32_dpp v212, v212, v212 row_bcast:15 row_mask:0xa bank_mask:0xf
	s_nop 1
	v_add_f32_dpp v212, v212, v212 row_bcast:31 row_mask:0xc bank_mask:0xf
	s_nop 1
	v_readlane_b32 s100, v212, 63
	s_nop 1
	v_fma_f32 v220, s100, v217, v216
	v_mul_f32_e32 v221, 0x4f800000, v220
	v_cmp_gt_f32_e32 vcc, v219, v220
	s_nop 1
	v_cndmask_b32_e32 v220, v220, v221, vcc
	v_sqrt_f32_e32 v221, v220
	s_nop 0
	v_add_u32_e32 v222, -1, v221
	v_add_u32_e32 v223, 1, v221
	v_fma_f32 v224, -v222, v221, v220
	v_fma_f32 v225, -v223, v221, v220
	v_cmp_ge_f32_e64 s[100:101], 0, v224
	s_nop 1
	v_cndmask_b32_e64 v221, v221, v222, s[100:101]
	v_cmp_lt_f32_e64 s[100:101], 0, v225
	s_nop 1
	v_cndmask_b32_e64 v221, v221, v223, s[100:101]
	v_mul_f32_e32 v222, 0x37800000, v221
	v_cndmask_b32_e32 v221, v221, v222, vcc
	v_cmp_class_f32_e32 vcc, v220, v218
	s_nop 1
	v_cndmask_b32_e32 v220, v221, v220, vcc
	v_div_scale_f32 v221, s[100:101], v220, v220, 1.0
	v_rcp_f32_e32 v223, v221
	v_div_scale_f32 v222, vcc, 1.0, v220, 1.0
	v_fma_f32 v224, -v221, v223, 1.0
	v_fmac_f32_e32 v223, v224, v223
	v_mul_f32_e32 v224, v222, v223
	v_fma_f32 v225, -v221, v224, v222
	v_fmac_f32_e32 v224, v225, v223
	v_fma_f32 v221, -v221, v224, v222
	v_div_fmas_f32 v221, v221, v223, v224
	v_div_fixup_f32 v221, v221, v220, 1.0
	v_mul_f32_e32 v226, v62, v221
	v_mul_f32_e32 v226, v226, v128
	v_mul_f32_e32 v227, v63, v221
	v_mul_f32_e32 v227, v227, v129
	v_mul_f32_e32 v228, v64, v221
	v_mul_f32_e32 v228, v228, v130
	v_mul_f32_e32 v229, v65, v221
	v_mul_f32_e32 v229, v229, v131
	v_cvt_pk_bf16_f32 v230, v226, v227
	v_cvt_pk_bf16_f32 v231, v228, v229
	global_store_dwordx2 v[200:201], v[230:231], off offset:0
	v_mul_f32_e32 v226, v66, v221
	v_mul_f32_e32 v226, v226, v132
	v_mul_f32_e32 v227, v67, v221
	v_mul_f32_e32 v227, v227, v133
	v_mul_f32_e32 v228, v68, v221
	v_mul_f32_e32 v228, v228, v134
	v_mul_f32_e32 v229, v69, v221
	v_mul_f32_e32 v229, v229, v135
	v_cvt_pk_bf16_f32 v232, v226, v227
	v_cvt_pk_bf16_f32 v233, v228, v229
	global_store_dwordx2 v[200:201], v[232:233], off offset:512
	v_mul_f32_e32 v226, v70, v221
	v_mul_f32_e32 v226, v226, v136
	v_mul_f32_e32 v227, v71, v221
	v_mul_f32_e32 v227, v227, v137
	v_mul_f32_e32 v228, v72, v221
	v_mul_f32_e32 v228, v228, v138
	v_mul_f32_e32 v229, v73, v221
	v_mul_f32_e32 v229, v229, v139
	v_cvt_pk_bf16_f32 v230, v226, v227
	v_cvt_pk_bf16_f32 v231, v228, v229
	global_store_dwordx2 v[200:201], v[230:231], off offset:1024
	v_mul_f32_e32 v226, v74, v221
	v_mul_f32_e32 v226, v226, v140
	v_mul_f32_e32 v227, v75, v221
	v_mul_f32_e32 v227, v227, v141
	v_mul_f32_e32 v228, v76, v221
	v_mul_f32_e32 v228, v228, v142
	v_mul_f32_e32 v229, v77, v221
	v_mul_f32_e32 v229, v229, v143
	v_cvt_pk_bf16_f32 v232, v226, v227
	v_cvt_pk_bf16_f32 v233, v228, v229
	global_store_dwordx2 v[200:201], v[232:233], off offset:1536
	v_mul_f32_e32 v226, v78, v221
	v_mul_f32_e32 v226, v226, v144
	v_mul_f32_e32 v227, v79, v221
	v_mul_f32_e32 v227, v227, v145
	v_mul_f32_e32 v228, v80, v221
	v_mul_f32_e32 v228, v228, v146
	v_mul_f32_e32 v229, v81, v221
	v_mul_f32_e32 v229, v229, v147
	v_cvt_pk_bf16_f32 v230, v226, v227
	v_cvt_pk_bf16_f32 v231, v228, v229
	global_store_dwordx2 v[200:201], v[230:231], off offset:2048
	v_mul_f32_e32 v226, v82, v221
	v_mul_f32_e32 v226, v226, v148
; #define GAS __attribute__((address_space(1)))
; __device__ __forceinline__ unsigned cvt_pk_bf16(float lo, float hi) { unsigned r; asm volatile("v_cvt_pk_bf16_f32 %0, %1, %2" : "=v"(r) : "v"(lo), "v"(hi)); return r; }
; __device__ __forceinline__ void rms_row_to_bf16(const float* xrow, const float* g, bf16_t* orow, int lane) {
;     ...
;     GAS u32x2* o8 = (GAS u32x2*)orow + lane;
; #pragma unroll
;     for (int j = 0; j < 16; ++j) { const f32x4 gg = gv[j]; u32x2 w; w.x = cvt_pk_bf16(v[j].x * rstd * gg.x, v[j].y * rstd * gg.y); w.y = cvt_pk_bf16(v[j].z * rstd * gg.z, v[j].w * rstd * gg.w); o8[64 * j] = w; }
	v_mul_f32_e32 v227, v83, v221
	v_mul_f32_e32 v227, v227, v149
	v_mul_f32_e32 v228, v84, v221
	v_mul_f32_e32 v228, v228, v150
	v_mul_f32_e32 v229, v85, v221
	v_mul_f32_e32 v229, v229, v151
	v_cvt_pk_bf16_f32 v232, v226, v227
	v_cvt_pk_bf16_f32 v233, v228, v229
	global_store_dwordx2 v[200:201], v[232:233], off offset:2560
	v_mul_f32_e32 v226, v86, v221
	v_mul_f32_e32 v226, v226, v152
	v_mul_f32_e32 v227, v87, v221
	v_mul_f32_e32 v227, v227, v153
	v_mul_f32_e32 v228, v88, v221
	v_mul_f32_e32 v228, v228, v154
	v_mul_f32_e32 v229, v89, v221
	v_mul_f32_e32 v229, v229, v155
	v_cvt_pk_bf16_f32 v230, v226, v227
	v_cvt_pk_bf16_f32 v231, v228, v229
	global_store_dwordx2 v[200:201], v[230:231], off offset:3072
	v_mul_f32_e32 v226, v90, v221
	v_mul_f32_e32 v226, v226, v156
	v_mul_f32_e32 v227, v91, v221
	v_mul_f32_e32 v227, v227, v157
	v_mul_f32_e32 v228, v92, v221
	v_mul_f32_e32 v228, v228, v158
	v_mul_f32_e32 v229, v93, v221
	v_mul_f32_e32 v229, v229, v159
	v_cvt_pk_bf16_f32 v232, v226, v227
	v_cvt_pk_bf16_f32 v233, v228, v229
	global_store_dwordx2 v[200:201], v[232:233], off offset:3584
	v_add_co_u32_e32 v200, vcc, 0x1000, v200
	s_nop 1
	v_addc_co_u32_e32 v201, vcc, 0, v201, vcc
	v_mul_f32_e32 v226, v94, v221
	v_mul_f32_e32 v226, v226, v160
	v_mul_f32_e32 v227, v95, v221
	v_mul_f32_e32 v227, v227, v161
	v_mul_f32_e32 v228, v96, v221
	v_mul_f32_e32 v228, v228, v162
	v_mul_f32_e32 v229, v97, v221
	v_mul_f32_e32 v229, v229, v163
	v_cvt_pk_bf16_f32 v230, v226, v227
	v_cvt_pk_bf16_f32 v231, v228, v229
	global_store_dwordx2 v[200:201], v[230:231], off offset:0
	v_mul_f32_e32 v226, v98, v221
	v_mul_f32_e32 v226, v226, v164
	v_mul_f32_e32 v227, v99, v221
	v_mul_f32_e32 v227, v227, v165
	v_mul_f32_e32 v228, v100, v221
	v_mul_f32_e32 v228, v228, v166
	v_mul_f32_e32 v229, v101, v221
	v_mul_f32_e32 v229, v229, v167
	v_cvt_pk_bf16_f32 v232, v226, v227
	v_cvt_pk_bf16_f32 v233, v228, v229
	global_store_dwordx2 v[200:201], v[232:233], off offset:512
	v_mul_f32_e32 v226, v102, v221
	v_mul_f32_e32 v226, v226, v168
	v_mul_f32_e32 v227, v103, v221
	v_mul_f32_e32 v227, v227, v169
	v_mul_f32_e32 v228, v104, v221
	v_mul_f32_e32 v228, v228, v170
	v_mul_f32_e32 v229, v105, v221
	v_mul_f32_e32 v229, v229, v171
	v_cvt_pk_bf16_f32 v230, v226, v227
	v_cvt_pk_bf16_f32 v231, v228, v229
	global_store_dwordx2 v[200:201], v[230:231], off offset:1024
	v_mul_f32_e32 v226, v106, v221
	v_mul_f32_e32 v226, v226, v172
	v_mul_f32_e32 v227, v107, v221
	v_mul_f32_e32 v227, v227, v173
	v_mul_f32_e32 v228, v108, v221
	v_mul_f32_e32 v228, v228, v174
	v_mul_f32_e32 v229, v109, v221
	v_mul_f32_e32 v229, v229, v175
	v_cvt_pk_bf16_f32 v232, v226, v227
	v_cvt_pk_bf16_f32 v233, v228, v229
	global_store_dwordx2 v[200:201], v[232:233], off offset:1536
	v_mul_f32_e32 v226, v110, v221
	v_mul_f32_e32 v226, v226, v176
	v_mul_f32_e32 v227, v111, v221
	v_mul_f32_e32 v227, v227, v177
	v_mul_f32_e32 v228, v112, v221
	v_mul_f32_e32 v228, v228, v178
	v_mul_f32_e32 v229, v113, v221
	v_mul_f32_e32 v229, v229, v179
	v_cvt_pk_bf16_f32 v230, v226, v227
	v_cvt_pk_bf16_f32 v231, v228, v229
	global_store_dwordx2 v[200:201], v[230:231], off offset:2048
	v_mul_f32_e32 v226, v114, v221
	v_mul_f32_e32 v226, v226, v180
	v_mul_f32_e32 v227, v115, v221
	v_mul_f32_e32 v227, v227, v181
	v_mul_f32_e32 v228, v116, v221
	v_mul_f32_e32 v228, v228, v182
	v_mul_f32_e32 v229, v117, v221
	v_mul_f32_e32 v229, v229, v183
	v_cvt_pk_bf16_f32 v232, v226, v227
	v_cvt_pk_bf16_f32 v233, v228, v229
	global_store_dwordx2 v[200:201], v[232:233], off offset:2560
	v_mul_f32_e32 v226, v118, v221
	v_mul_f32_e32 v226, v226, v184
	v_mul_f32_e32 v227, v119, v221
	v_mul_f32_e32 v227, v227, v185
	v_mul_f32_e32 v228, v120, v221
	v_mul_f32_e32 v228, v228, v186
	v_mul_f32_e32 v229, v121, v221
	v_mul_f32_e32 v229, v229, v187
	v_cvt_pk_bf16_f32 v230, v226, v227
	v_cvt_pk_bf16_f32 v231, v228, v229
	global_store_dwordx2 v[200:201], v[230:231], off offset:3072
	v_mul_f32_e32 v226, v122, v221
	v_mul_f32_e32 v226, v226, v188
	v_mul_f32_e32 v227, v123, v221
	v_mul_f32_e32 v227, v227, v189
	v_mul_f32_e32 v228, v124, v221
	v_mul_f32_e32 v228, v228, v190
	v_mul_f32_e32 v229, v125, v221
	v_mul_f32_e32 v229, v229, v191
	v_cvt_pk_bf16_f32 v232, v226, v227
	v_cvt_pk_bf16_f32 v233, v228, v229
	global_store_dwordx2 v[200:201], v[232:233], off offset:3584
	s_add_u32 s99, s99, 0x100
	s_cmpk_lt_u32 s99, 0x400
	s_cbranch_scc1 .Lhm_row
	s_waitcnt vmcnt(0)
	s_barrier
	s_mov_b64 exec, s[14:15]
	s_cbranch_execz .Lkv_pub_done
	buffer_wbl2 sc1
	s_waitcnt vmcnt(0)
	s_add_u32 s100, s6, 0x8080
	s_addc_u32 s101, s7, 0
	v_mov_b32_e32 v3, 0
	v_mov_b32_e32 v2, 1
	global_atomic_add v3, v2, s[100:101]
	s_waitcnt vmcnt(0)
